# v11: plus 8-deep residual prefetch in the down-projection (P_J) epilogue
# baseline (speedup 1.0000x reference)
; DI unsigned pk2(float lo, float hi) { f32x2 v = {lo, hi}; bf16x2_t b = __builtin_convertvector(v, bf16x2_t); return __builtin_bit_cast(unsigned, b); }
;     DI void operator()(const f32x4 (&acc)[2][2][4][2], const Unit& u, int wr, int wc, int fr, int fq) const {
;     ...
;         EPI_ROWS_BEGIN
;             float ss = 0.f;
; #pragma unroll
;             for (int bj = 0; bj < 2; ++bj) { const int col = colb + bj * HALF; bf16_t* xp = XB + (size_t)row * DM + col;
;                 float xv[8]; unpack8(*(const u32x4*)xp, xv);
;                 const f32x4 x0 = (f32x4){xv[0], xv[1], xv[2], xv[3]} + acc[ai][bj][m][0], x1 = (f32x4){xv[4], xv[5], xv[6], xv[7]} + acc[ai][bj][m][1];
;                 if (Y != nullptr) { float* yp = Y + (size_t)row * DM + col; *(f32x4*)yp = x0; *(f32x4*)(yp + 4) = x1; }
;                 u32x4 w; w.x = pk2(x0[0], x0[1]); w.y = pk2(x0[2], x0[3]); w.z = pk2(x1[0], x1[1]); w.w = pk2(x1[2], x1[3]); *(u32x4*)xp = w;
;                 ss += (x0[0] * x0[0] + x0[1] * x0[1]) + (x0[2] * x0[2] + x0[3] * x0[3]) + (x1[0] * x1[0] + x1[1] * x1[1]) + (x1[2] * x1[2] + x1[3] * x1[3]); }
.LBB0_3290:
	v_lshl_add_u32 v142, s58, 8, v148
	v_ashrrev_i32_e32 v143, 31, v142
	v_lshl_or_b32 v140, s57, 8, v162
	v_lshlrev_b64 v[144:145], 11, v[142:143]
	v_lshl_add_u64 v[144:145], s[10:11], 0, v[144:145]
	v_ashrrev_i32_e32 v141, 31, v140
	v_lshl_add_u64 v[144:145], v[140:141], 1, v[144:145]
	v_mov_b32_e32 v214, 0x8000
	v_mov_b32_e32 v215, 0
	global_load_dwordx4 v[168:171], v[144:145], off
	global_load_dwordx4 v[172:175], v[144:145], off offset:256
	v_lshl_add_u64 v[216:217], v[214:215], 0, v[144:145]
	global_load_dwordx4 v[176:179], v[216:217], off
	global_load_dwordx4 v[180:183], v[216:217], off offset:256
	v_lshl_add_u64 v[216:217], v[214:215], 1, v[144:145]
	global_load_dwordx4 v[184:187], v[216:217], off
	global_load_dwordx4 v[188:191], v[216:217], off offset:256
	v_lshl_add_u64 v[216:217], v[214:215], 0, v[216:217]
	global_load_dwordx4 v[192:195], v[216:217], off
	global_load_dwordx4 v[196:199], v[216:217], off offset:256
	v_lshl_add_u64 v[200:201], v[214:215], 3, v[144:145]
	v_lshl_add_u64 v[202:203], v[214:215], 0, v[200:201]
	v_lshl_add_u64 v[210:211], v[214:215], 1, v[200:201]
	v_lshl_add_u64 v[212:213], v[214:215], 0, v[210:211]
	v_cndmask_b32_e64 v146, 0, 1, s[24:25]
	v_cmp_ne_u32_e64 s[36:37], 1, v146
	v_lshlrev_b64 v[146:147], 10, v[142:143]
	s_andn2_b64 vcc, exec, s[24:25]
	v_lshl_add_u64 v[146:147], v[146:147], 2, s[8:9]
	s_waitcnt vmcnt(7)
	v_mov_b64_e32 v[150:151], v[168:169]
	v_mov_b64_e32 v[152:153], v[170:171]
	global_load_dwordx4 v[168:171], v[200:201], off
	v_lshlrev_b32_e32 v164, 16, v150
	v_and_b32_e32 v165, 0xffff0000, v150
	v_lshlrev_b32_e32 v150, 16, v151
	v_and_b32_e32 v151, 0xffff0000, v151
	v_lshlrev_b32_e32 v166, 16, v152
	v_and_b32_e32 v167, 0xffff0000, v152
	v_lshlrev_b32_e32 v152, 16, v153
	v_and_b32_e32 v153, 0xffff0000, v153
	v_pk_add_f32 v[128:129], v[128:129], v[150:151]
	v_pk_add_f32 v[126:127], v[126:127], v[164:165]
	v_pk_add_f32 v[124:125], v[124:125], v[152:153]
	v_pk_add_f32 v[122:123], v[122:123], v[166:167]
	s_cbranch_vccnz .LBB0_3292
	v_lshl_add_u64 v[150:151], v[140:141], 2, v[146:147]
	global_store_dwordx4 v[150:151], v[126:129], off
	global_store_dwordx4 v[150:151], v[122:125], off offset:16
.LBB0_3292:
	v_cvt_pk_bf16_f32 v164, v126, v127
	v_cvt_pk_bf16_f32 v165, v128, v129
	v_cvt_pk_bf16_f32 v166, v122, v123
	v_cvt_pk_bf16_f32 v167, v124, v125
	global_store_dwordx4 v[144:145], v[164:167], off
	s_and_b64 vcc, exec, s[36:37]
	s_waitcnt vmcnt(8)
	v_mov_b64_e32 v[150:151], v[172:173]
	v_mov_b64_e32 v[152:153], v[174:175]
	global_load_dwordx4 v[172:175], v[200:201], off offset:256
	v_lshlrev_b32_e32 v164, 16, v150
	v_and_b32_e32 v165, 0xffff0000, v150
	v_lshlrev_b32_e32 v150, 16, v151
	v_and_b32_e32 v151, 0xffff0000, v151
	v_lshlrev_b32_e32 v166, 16, v152
	v_and_b32_e32 v167, 0xffff0000, v152
	v_lshlrev_b32_e32 v152, 16, v153
	v_and_b32_e32 v153, 0xffff0000, v153
	v_pk_add_f32 v[120:121], v[120:121], v[150:151]
	v_pk_add_f32 v[118:119], v[118:119], v[164:165]
	v_pk_add_f32 v[116:117], v[116:117], v[152:153]
	v_pk_add_f32 v[114:115], v[114:115], v[166:167]
	s_cbranch_vccnz .LBB0_3294
	v_lshl_add_u64 v[146:147], v[140:141], 2, v[146:147]
	global_store_dwordx4 v[146:147], v[118:121], off offset:512
	global_store_dwordx4 v[146:147], v[114:117], off offset:528

; DI unsigned pk2(float lo, float hi) { f32x2 v = {lo, hi}; bf16x2_t b = __builtin_convertvector(v, bf16x2_t); return __builtin_bit_cast(unsigned, b); }
;     DI void operator()(const f32x4 (&acc)[2][2][4][2], const Unit& u, int wr, int wc, int fr, int fq) const {
;     ...
;         EPI_ROWS_BEGIN
;             float ss = 0.f;
; #pragma unroll
;             for (int bj = 0; bj < 2; ++bj) { const int col = colb + bj * HALF; bf16_t* xp = XB + (size_t)row * DM + col;
;                 float xv[8]; unpack8(*(const u32x4*)xp, xv);
;                 const f32x4 x0 = (f32x4){xv[0], xv[1], xv[2], xv[3]} + acc[ai][bj][m][0], x1 = (f32x4){xv[4], xv[5], xv[6], xv[7]} + acc[ai][bj][m][1];
;                 if (Y != nullptr) { float* yp = Y + (size_t)row * DM + col; *(f32x4*)yp = x0; *(f32x4*)(yp + 4) = x1; }
;                 u32x4 w; w.x = pk2(x0[0], x0[1]); w.y = pk2(x0[2], x0[3]); w.z = pk2(x1[0], x1[1]); w.w = pk2(x1[2], x1[3]); *(u32x4*)xp = w;
;                 ss += (x0[0] * x0[0] + x0[1] * x0[1]) + (x0[2] * x0[2] + x0[3] * x0[3]) + (x1[0] * x1[0] + x1[1] * x1[1]) + (x1[2] * x1[2] + x1[3] * x1[3]); }
.LBB0_3296:
	s_or_b64 exec, exec, s[38:39]
	v_or_b32_e32 v122, 16, v142
	v_ashrrev_i32_e32 v123, 31, v122
	v_lshlrev_b64 v[116:117], 11, v[122:123]
	v_lshl_add_u64 v[116:117], s[10:11], 0, v[116:117]
	v_lshl_add_u64 v[116:117], v[140:141], 1, v[116:117]
	s_waitcnt lgkmcnt(0)
	v_lshlrev_b64 v[122:123], 10, v[122:123]
	s_and_b64 vcc, exec, s[36:37]
	s_waitcnt vmcnt(9)
	v_mov_b64_e32 v[118:119], v[176:177]
	v_mov_b64_e32 v[120:121], v[178:179]
	global_load_dwordx4 v[176:179], v[202:203], off
	v_lshlrev_b32_e32 v124, 16, v118
	v_and_b32_e32 v125, 0xffff0000, v118
	v_lshlrev_b32_e32 v118, 16, v119
	v_and_b32_e32 v119, 0xffff0000, v119
	v_lshlrev_b32_e32 v126, 16, v120
	v_and_b32_e32 v127, 0xffff0000, v120
	v_lshlrev_b32_e32 v120, 16, v121
	v_and_b32_e32 v121, 0xffff0000, v121
	v_pk_add_f32 v[112:113], v[112:113], v[118:119]
	v_pk_add_f32 v[110:111], v[110:111], v[124:125]
	v_pk_add_f32 v[108:109], v[108:109], v[120:121]
	v_pk_add_f32 v[106:107], v[106:107], v[126:127]
	v_lshl_add_u64 v[118:119], v[122:123], 2, s[8:9]
	s_cbranch_vccnz .LBB0_3298
	v_lshl_add_u64 v[120:121], v[140:141], 2, v[118:119]
	global_store_dwordx4 v[120:121], v[110:113], off
	global_store_dwordx4 v[120:121], v[106:109], off offset:16
.LBB0_3298:
	v_cvt_pk_bf16_f32 v124, v110, v111
	v_cvt_pk_bf16_f32 v125, v112, v113
	v_cvt_pk_bf16_f32 v126, v106, v107
	v_cvt_pk_bf16_f32 v127, v108, v109
	global_store_dwordx4 v[116:117], v[124:127], off
	s_and_b64 vcc, exec, s[36:37]
	s_waitcnt vmcnt(10)
	v_mov_b64_e32 v[120:121], v[180:181]
	v_mov_b64_e32 v[122:123], v[182:183]
	global_load_dwordx4 v[180:183], v[202:203], off offset:256
	v_lshlrev_b32_e32 v124, 16, v120
	v_and_b32_e32 v125, 0xffff0000, v120
	v_lshlrev_b32_e32 v120, 16, v121
	v_and_b32_e32 v121, 0xffff0000, v121
	v_lshlrev_b32_e32 v126, 16, v122
	v_and_b32_e32 v127, 0xffff0000, v122
	v_lshlrev_b32_e32 v122, 16, v123
	v_and_b32_e32 v123, 0xffff0000, v123
	v_pk_add_f32 v[104:105], v[104:105], v[120:121]
	v_pk_add_f32 v[102:103], v[102:103], v[124:125]
	v_pk_add_f32 v[100:101], v[100:101], v[122:123]
	v_pk_add_f32 v[98:99], v[98:99], v[126:127]
	s_cbranch_vccnz .LBB0_3300
	v_lshl_add_u64 v[118:119], v[140:141], 2, v[118:119]
	global_store_dwordx4 v[118:119], v[102:105], off offset:512
	global_store_dwordx4 v[118:119], v[98:101], off offset:528

; DI unsigned pk2(float lo, float hi) { f32x2 v = {lo, hi}; bf16x2_t b = __builtin_convertvector(v, bf16x2_t); return __builtin_bit_cast(unsigned, b); }
;     DI void operator()(const f32x4 (&acc)[2][2][4][2], const Unit& u, int wr, int wc, int fr, int fq) const {
;     ...
;         EPI_ROWS_BEGIN
;             float ss = 0.f;
; #pragma unroll
;             for (int bj = 0; bj < 2; ++bj) { const int col = colb + bj * HALF; bf16_t* xp = XB + (size_t)row * DM + col;
;                 float xv[8]; unpack8(*(const u32x4*)xp, xv);
;                 const f32x4 x0 = (f32x4){xv[0], xv[1], xv[2], xv[3]} + acc[ai][bj][m][0], x1 = (f32x4){xv[4], xv[5], xv[6], xv[7]} + acc[ai][bj][m][1];
;                 if (Y != nullptr) { float* yp = Y + (size_t)row * DM + col; *(f32x4*)yp = x0; *(f32x4*)(yp + 4) = x1; }
;                 u32x4 w; w.x = pk2(x0[0], x0[1]); w.y = pk2(x0[2], x0[3]); w.z = pk2(x1[0], x1[1]); w.w = pk2(x1[2], x1[3]); *(u32x4*)xp = w;
;                 ss += (x0[0] * x0[0] + x0[1] * x0[1]) + (x0[2] * x0[2] + x0[3] * x0[3]) + (x1[0] * x1[0] + x1[1] * x1[1]) + (x1[2] * x1[2] + x1[3] * x1[3]); }
.LBB0_3302:
	s_or_b64 exec, exec, s[38:39]
	v_or_b32_e32 v104, 32, v142
	v_ashrrev_i32_e32 v105, 31, v104
	v_lshlrev_b64 v[98:99], 11, v[104:105]
	v_lshl_add_u64 v[98:99], s[10:11], 0, v[98:99]
	v_lshl_add_u64 v[98:99], v[140:141], 1, v[98:99]
	s_waitcnt lgkmcnt(0)
	v_lshlrev_b64 v[104:105], 10, v[104:105]
	s_and_b64 vcc, exec, s[36:37]
	s_waitcnt vmcnt(11)
	v_mov_b64_e32 v[100:101], v[184:185]
	v_mov_b64_e32 v[102:103], v[186:187]
	global_load_dwordx4 v[184:187], v[210:211], off
	v_lshlrev_b32_e32 v106, 16, v100
	v_and_b32_e32 v107, 0xffff0000, v100
	v_lshlrev_b32_e32 v100, 16, v101
	v_and_b32_e32 v101, 0xffff0000, v101
	v_lshlrev_b32_e32 v108, 16, v102
	v_and_b32_e32 v109, 0xffff0000, v102
	v_lshlrev_b32_e32 v102, 16, v103
	v_and_b32_e32 v103, 0xffff0000, v103
	v_pk_add_f32 v[94:95], v[94:95], v[100:101]
	v_pk_add_f32 v[92:93], v[92:93], v[106:107]
	v_pk_add_f32 v[90:91], v[90:91], v[102:103]
	v_pk_add_f32 v[88:89], v[88:89], v[108:109]
	v_lshl_add_u64 v[100:101], v[104:105], 2, s[8:9]
	s_cbranch_vccnz .LBB0_3304
	v_lshl_add_u64 v[102:103], v[140:141], 2, v[100:101]
	global_store_dwordx4 v[102:103], v[92:95], off
	global_store_dwordx4 v[102:103], v[88:91], off offset:16
.LBB0_3304:
	v_cvt_pk_bf16_f32 v106, v92, v93
	v_cvt_pk_bf16_f32 v107, v94, v95
	v_cvt_pk_bf16_f32 v108, v88, v89
	v_cvt_pk_bf16_f32 v109, v90, v91
	global_store_dwordx4 v[98:99], v[106:109], off
	s_and_b64 vcc, exec, s[36:37]
	s_waitcnt vmcnt(12)
	v_mov_b64_e32 v[102:103], v[188:189]
	v_mov_b64_e32 v[104:105], v[190:191]
	global_load_dwordx4 v[188:191], v[210:211], off offset:256
	v_lshlrev_b32_e32 v106, 16, v102
	v_and_b32_e32 v107, 0xffff0000, v102
	v_lshlrev_b32_e32 v102, 16, v103
	v_and_b32_e32 v103, 0xffff0000, v103
	v_lshlrev_b32_e32 v108, 16, v104
	v_and_b32_e32 v109, 0xffff0000, v104
	v_lshlrev_b32_e32 v104, 16, v105
	v_and_b32_e32 v105, 0xffff0000, v105
	v_pk_add_f32 v[86:87], v[86:87], v[102:103]
	v_pk_add_f32 v[84:85], v[84:85], v[106:107]
	v_pk_add_f32 v[82:83], v[82:83], v[104:105]
	v_pk_add_f32 v[80:81], v[80:81], v[108:109]
	s_cbranch_vccnz .LBB0_3306
	v_lshl_add_u64 v[100:101], v[140:141], 2, v[100:101]
	global_store_dwordx4 v[100:101], v[84:87], off offset:512
	global_store_dwordx4 v[100:101], v[80:83], off offset:528

; DI unsigned pk2(float lo, float hi) { f32x2 v = {lo, hi}; bf16x2_t b = __builtin_convertvector(v, bf16x2_t); return __builtin_bit_cast(unsigned, b); }
;     DI void operator()(const f32x4 (&acc)[2][2][4][2], const Unit& u, int wr, int wc, int fr, int fq) const {
;     ...
;         EPI_ROWS_BEGIN
;             float ss = 0.f;
; #pragma unroll
;             for (int bj = 0; bj < 2; ++bj) { const int col = colb + bj * HALF; bf16_t* xp = XB + (size_t)row * DM + col;
;                 float xv[8]; unpack8(*(const u32x4*)xp, xv);
;                 const f32x4 x0 = (f32x4){xv[0], xv[1], xv[2], xv[3]} + acc[ai][bj][m][0], x1 = (f32x4){xv[4], xv[5], xv[6], xv[7]} + acc[ai][bj][m][1];
;                 if (Y != nullptr) { float* yp = Y + (size_t)row * DM + col; *(f32x4*)yp = x0; *(f32x4*)(yp + 4) = x1; }
;                 u32x4 w; w.x = pk2(x0[0], x0[1]); w.y = pk2(x0[2], x0[3]); w.z = pk2(x1[0], x1[1]); w.w = pk2(x1[2], x1[3]); *(u32x4*)xp = w;
;                 ss += (x0[0] * x0[0] + x0[1] * x0[1]) + (x0[2] * x0[2] + x0[3] * x0[3]) + (x1[0] * x1[0] + x1[1] * x1[1]) + (x1[2] * x1[2] + x1[3] * x1[3]); }
.LBB0_3308:
	s_or_b64 exec, exec, s[38:39]
	v_or_b32_e32 v86, 48, v142
	v_ashrrev_i32_e32 v87, 31, v86
	v_lshlrev_b64 v[80:81], 11, v[86:87]
	v_lshl_add_u64 v[80:81], s[10:11], 0, v[80:81]
	v_lshl_add_u64 v[80:81], v[140:141], 1, v[80:81]
	s_waitcnt lgkmcnt(0)
	v_lshlrev_b64 v[86:87], 10, v[86:87]
	s_and_b64 vcc, exec, s[36:37]
	s_waitcnt vmcnt(13)
	v_mov_b64_e32 v[82:83], v[192:193]
	v_mov_b64_e32 v[84:85], v[194:195]
	global_load_dwordx4 v[192:195], v[212:213], off
	v_lshlrev_b32_e32 v88, 16, v82
	v_and_b32_e32 v89, 0xffff0000, v82
	v_lshlrev_b32_e32 v82, 16, v83
	v_and_b32_e32 v83, 0xffff0000, v83
	v_lshlrev_b32_e32 v90, 16, v84
	v_and_b32_e32 v91, 0xffff0000, v84
	v_lshlrev_b32_e32 v84, 16, v85
	v_and_b32_e32 v85, 0xffff0000, v85
	v_pk_add_f32 v[78:79], v[78:79], v[82:83]
	v_pk_add_f32 v[76:77], v[76:77], v[88:89]
	v_pk_add_f32 v[74:75], v[74:75], v[84:85]
	v_pk_add_f32 v[72:73], v[72:73], v[90:91]
	v_lshl_add_u64 v[82:83], v[86:87], 2, s[8:9]
	s_cbranch_vccnz .LBB0_3310
	v_lshl_add_u64 v[84:85], v[140:141], 2, v[82:83]
	global_store_dwordx4 v[84:85], v[76:79], off
	global_store_dwordx4 v[84:85], v[72:75], off offset:16
.LBB0_3310:
	v_cvt_pk_bf16_f32 v88, v76, v77
	v_cvt_pk_bf16_f32 v89, v78, v79
	v_cvt_pk_bf16_f32 v90, v72, v73
	v_cvt_pk_bf16_f32 v91, v74, v75
	global_store_dwordx4 v[80:81], v[88:91], off
	s_and_b64 vcc, exec, s[36:37]
	s_waitcnt vmcnt(14)
	v_mov_b64_e32 v[84:85], v[196:197]
	v_mov_b64_e32 v[86:87], v[198:199]
	global_load_dwordx4 v[196:199], v[212:213], off offset:256
	v_lshlrev_b32_e32 v88, 16, v84
	v_and_b32_e32 v89, 0xffff0000, v84
	v_lshlrev_b32_e32 v84, 16, v85
	v_and_b32_e32 v85, 0xffff0000, v85
	v_lshlrev_b32_e32 v90, 16, v86
	v_and_b32_e32 v91, 0xffff0000, v86
	v_lshlrev_b32_e32 v86, 16, v87
	v_and_b32_e32 v87, 0xffff0000, v87
	v_pk_add_f32 v[70:71], v[70:71], v[84:85]
	v_pk_add_f32 v[68:69], v[68:69], v[88:89]
	v_pk_add_f32 v[66:67], v[66:67], v[86:87]
	v_pk_add_f32 v[64:65], v[64:65], v[90:91]
	s_cbranch_vccnz .LBB0_3312
	v_lshl_add_u64 v[82:83], v[140:141], 2, v[82:83]
	global_store_dwordx4 v[82:83], v[68:71], off offset:512
	global_store_dwordx4 v[82:83], v[64:67], off offset:528

; DI unsigned pk2(float lo, float hi) { f32x2 v = {lo, hi}; bf16x2_t b = __builtin_convertvector(v, bf16x2_t); return __builtin_bit_cast(unsigned, b); }
;     DI void operator()(const f32x4 (&acc)[2][2][4][2], const Unit& u, int wr, int wc, int fr, int fq) const {
;     ...
;         EPI_ROWS_BEGIN
;             float ss = 0.f;
; #pragma unroll
;             for (int bj = 0; bj < 2; ++bj) { const int col = colb + bj * HALF; bf16_t* xp = XB + (size_t)row * DM + col;
;                 float xv[8]; unpack8(*(const u32x4*)xp, xv);
;                 const f32x4 x0 = (f32x4){xv[0], xv[1], xv[2], xv[3]} + acc[ai][bj][m][0], x1 = (f32x4){xv[4], xv[5], xv[6], xv[7]} + acc[ai][bj][m][1];
;                 if (Y != nullptr) { float* yp = Y + (size_t)row * DM + col; *(f32x4*)yp = x0; *(f32x4*)(yp + 4) = x1; }
;                 u32x4 w; w.x = pk2(x0[0], x0[1]); w.y = pk2(x0[2], x0[3]); w.z = pk2(x1[0], x1[1]); w.w = pk2(x1[2], x1[3]); *(u32x4*)xp = w;
;                 ss += (x0[0] * x0[0] + x0[1] * x0[1]) + (x0[2] * x0[2] + x0[3] * x0[3]) + (x1[0] * x1[0] + x1[1] * x1[1]) + (x1[2] * x1[2] + x1[3] * x1[3]); }
.LBB0_3314:
	s_or_b64 exec, exec, s[38:39]
	v_add_u32_e32 v70, 0x80, v142
	v_ashrrev_i32_e32 v71, 31, v70
	v_lshlrev_b64 v[64:65], 11, v[70:71]
	v_lshl_add_u64 v[64:65], s[10:11], 0, v[64:65]
	v_lshl_add_u64 v[64:65], v[140:141], 1, v[64:65]
	s_waitcnt lgkmcnt(0)
	v_lshlrev_b64 v[70:71], 10, v[70:71]
	s_and_b64 vcc, exec, s[36:37]
	s_waitcnt vmcnt(15)
	v_mov_b64_e32 v[66:67], v[168:169]
	v_mov_b64_e32 v[68:69], v[170:171]
	v_lshlrev_b32_e32 v72, 16, v66
	v_and_b32_e32 v73, 0xffff0000, v66
	v_lshlrev_b32_e32 v66, 16, v67
	v_and_b32_e32 v67, 0xffff0000, v67
	v_lshlrev_b32_e32 v74, 16, v68
	v_and_b32_e32 v75, 0xffff0000, v68
	v_lshlrev_b32_e32 v68, 16, v69
	v_and_b32_e32 v69, 0xffff0000, v69
	v_pk_add_f32 v[62:63], v[62:63], v[66:67]
	v_pk_add_f32 v[60:61], v[60:61], v[72:73]
	v_pk_add_f32 v[58:59], v[58:59], v[68:69]
	v_pk_add_f32 v[56:57], v[56:57], v[74:75]
	v_lshl_add_u64 v[66:67], v[70:71], 2, s[8:9]
	s_cbranch_vccnz .LBB0_3316
	v_lshl_add_u64 v[68:69], v[140:141], 2, v[66:67]
	global_store_dwordx4 v[68:69], v[60:63], off
	global_store_dwordx4 v[68:69], v[56:59], off offset:16
.LBB0_3316:
	v_cvt_pk_bf16_f32 v72, v60, v61
	v_cvt_pk_bf16_f32 v73, v62, v63
	v_cvt_pk_bf16_f32 v74, v56, v57
	v_cvt_pk_bf16_f32 v75, v58, v59
	global_store_dwordx4 v[64:65], v[72:75], off
	s_and_b64 vcc, exec, s[36:37]
	s_waitcnt vmcnt(14)
	v_mov_b64_e32 v[68:69], v[172:173]
	v_mov_b64_e32 v[70:71], v[174:175]
	v_lshlrev_b32_e32 v72, 16, v68
	v_and_b32_e32 v73, 0xffff0000, v68
	v_lshlrev_b32_e32 v68, 16, v69
	v_and_b32_e32 v69, 0xffff0000, v69
	v_lshlrev_b32_e32 v74, 16, v70
	v_and_b32_e32 v75, 0xffff0000, v70
	v_lshlrev_b32_e32 v70, 16, v71
	v_and_b32_e32 v71, 0xffff0000, v71
	v_pk_add_f32 v[54:55], v[54:55], v[68:69]
	v_pk_add_f32 v[52:53], v[52:53], v[72:73]
	v_pk_add_f32 v[50:51], v[50:51], v[70:71]
	v_pk_add_f32 v[48:49], v[48:49], v[74:75]
	s_cbranch_vccnz .LBB0_3318
	v_lshl_add_u64 v[66:67], v[140:141], 2, v[66:67]
	global_store_dwordx4 v[66:67], v[52:55], off offset:512
	global_store_dwordx4 v[66:67], v[48:51], off offset:528

; DI unsigned pk2(float lo, float hi) { f32x2 v = {lo, hi}; bf16x2_t b = __builtin_convertvector(v, bf16x2_t); return __builtin_bit_cast(unsigned, b); }
;     DI void operator()(const f32x4 (&acc)[2][2][4][2], const Unit& u, int wr, int wc, int fr, int fq) const {
;     ...
;         EPI_ROWS_BEGIN
;             float ss = 0.f;
; #pragma unroll
;             for (int bj = 0; bj < 2; ++bj) { const int col = colb + bj * HALF; bf16_t* xp = XB + (size_t)row * DM + col;
;                 float xv[8]; unpack8(*(const u32x4*)xp, xv);
;                 const f32x4 x0 = (f32x4){xv[0], xv[1], xv[2], xv[3]} + acc[ai][bj][m][0], x1 = (f32x4){xv[4], xv[5], xv[6], xv[7]} + acc[ai][bj][m][1];
;                 if (Y != nullptr) { float* yp = Y + (size_t)row * DM + col; *(f32x4*)yp = x0; *(f32x4*)(yp + 4) = x1; }
;                 u32x4 w; w.x = pk2(x0[0], x0[1]); w.y = pk2(x0[2], x0[3]); w.z = pk2(x1[0], x1[1]); w.w = pk2(x1[2], x1[3]); *(u32x4*)xp = w;
;                 ss += (x0[0] * x0[0] + x0[1] * x0[1]) + (x0[2] * x0[2] + x0[3] * x0[3]) + (x1[0] * x1[0] + x1[1] * x1[1]) + (x1[2] * x1[2] + x1[3] * x1[3]); }
.LBB0_3320:
	s_or_b64 exec, exec, s[38:39]
	v_add_u32_e32 v54, 0x90, v142
	v_ashrrev_i32_e32 v55, 31, v54
	v_lshlrev_b64 v[48:49], 11, v[54:55]
	v_lshl_add_u64 v[48:49], s[10:11], 0, v[48:49]
	v_lshl_add_u64 v[48:49], v[140:141], 1, v[48:49]
	s_waitcnt lgkmcnt(0)
	v_lshlrev_b64 v[54:55], 10, v[54:55]
	s_and_b64 vcc, exec, s[36:37]
	s_waitcnt vmcnt(13)
	v_mov_b64_e32 v[50:51], v[176:177]
	v_mov_b64_e32 v[52:53], v[178:179]
	v_lshlrev_b32_e32 v56, 16, v50
	v_and_b32_e32 v57, 0xffff0000, v50
	v_lshlrev_b32_e32 v50, 16, v51
	v_and_b32_e32 v51, 0xffff0000, v51
	v_lshlrev_b32_e32 v58, 16, v52
	v_and_b32_e32 v59, 0xffff0000, v52
	v_lshlrev_b32_e32 v52, 16, v53
	v_and_b32_e32 v53, 0xffff0000, v53
	v_pk_add_f32 v[46:47], v[46:47], v[50:51]
	v_pk_add_f32 v[44:45], v[44:45], v[56:57]
	v_pk_add_f32 v[42:43], v[42:43], v[52:53]
	v_pk_add_f32 v[40:41], v[40:41], v[58:59]
	v_lshl_add_u64 v[50:51], v[54:55], 2, s[8:9]
	s_cbranch_vccnz .LBB0_3322
	v_lshl_add_u64 v[52:53], v[140:141], 2, v[50:51]
	global_store_dwordx4 v[52:53], v[44:47], off
	global_store_dwordx4 v[52:53], v[40:43], off offset:16
.LBB0_3322:
	v_cvt_pk_bf16_f32 v56, v44, v45
	v_cvt_pk_bf16_f32 v57, v46, v47
	v_cvt_pk_bf16_f32 v58, v40, v41
	v_cvt_pk_bf16_f32 v59, v42, v43
	global_store_dwordx4 v[48:49], v[56:59], off
	s_and_b64 vcc, exec, s[36:37]
	s_waitcnt vmcnt(12)
	v_mov_b64_e32 v[52:53], v[180:181]
	v_mov_b64_e32 v[54:55], v[182:183]
	v_lshlrev_b32_e32 v56, 16, v52
	v_and_b32_e32 v57, 0xffff0000, v52
	v_lshlrev_b32_e32 v52, 16, v53
	v_and_b32_e32 v53, 0xffff0000, v53
	v_lshlrev_b32_e32 v58, 16, v54
	v_and_b32_e32 v59, 0xffff0000, v54
	v_lshlrev_b32_e32 v54, 16, v55
	v_and_b32_e32 v55, 0xffff0000, v55
	v_pk_add_f32 v[38:39], v[38:39], v[52:53]
	v_pk_add_f32 v[36:37], v[36:37], v[56:57]
	v_pk_add_f32 v[34:35], v[34:35], v[54:55]
	v_pk_add_f32 v[32:33], v[32:33], v[58:59]
	s_cbranch_vccnz .LBB0_3324
	v_lshl_add_u64 v[50:51], v[140:141], 2, v[50:51]
	global_store_dwordx4 v[50:51], v[36:39], off offset:512
	global_store_dwordx4 v[50:51], v[32:35], off offset:528

; DI unsigned pk2(float lo, float hi) { f32x2 v = {lo, hi}; bf16x2_t b = __builtin_convertvector(v, bf16x2_t); return __builtin_bit_cast(unsigned, b); }
;     DI void operator()(const f32x4 (&acc)[2][2][4][2], const Unit& u, int wr, int wc, int fr, int fq) const {
;     ...
;         EPI_ROWS_BEGIN
;             float ss = 0.f;
; #pragma unroll
;             for (int bj = 0; bj < 2; ++bj) { const int col = colb + bj * HALF; bf16_t* xp = XB + (size_t)row * DM + col;
;                 float xv[8]; unpack8(*(const u32x4*)xp, xv);
;                 const f32x4 x0 = (f32x4){xv[0], xv[1], xv[2], xv[3]} + acc[ai][bj][m][0], x1 = (f32x4){xv[4], xv[5], xv[6], xv[7]} + acc[ai][bj][m][1];
;                 if (Y != nullptr) { float* yp = Y + (size_t)row * DM + col; *(f32x4*)yp = x0; *(f32x4*)(yp + 4) = x1; }
;                 u32x4 w; w.x = pk2(x0[0], x0[1]); w.y = pk2(x0[2], x0[3]); w.z = pk2(x1[0], x1[1]); w.w = pk2(x1[2], x1[3]); *(u32x4*)xp = w;
;                 ss += (x0[0] * x0[0] + x0[1] * x0[1]) + (x0[2] * x0[2] + x0[3] * x0[3]) + (x1[0] * x1[0] + x1[1] * x1[1]) + (x1[2] * x1[2] + x1[3] * x1[3]); }
.LBB0_3326:
	s_or_b64 exec, exec, s[38:39]
	v_add_u32_e32 v38, 0xa0, v142
	v_ashrrev_i32_e32 v39, 31, v38
	v_lshlrev_b64 v[32:33], 11, v[38:39]
	v_lshl_add_u64 v[32:33], s[10:11], 0, v[32:33]
	v_lshl_add_u64 v[32:33], v[140:141], 1, v[32:33]
	s_waitcnt lgkmcnt(0)
	v_lshlrev_b64 v[38:39], 10, v[38:39]
	s_and_b64 vcc, exec, s[36:37]
	s_waitcnt vmcnt(11)
	v_mov_b64_e32 v[34:35], v[184:185]
	v_mov_b64_e32 v[36:37], v[186:187]
	v_lshlrev_b32_e32 v40, 16, v34
	v_and_b32_e32 v41, 0xffff0000, v34
	v_lshlrev_b32_e32 v34, 16, v35
	v_and_b32_e32 v35, 0xffff0000, v35
	v_lshlrev_b32_e32 v42, 16, v36
	v_and_b32_e32 v43, 0xffff0000, v36
	v_lshlrev_b32_e32 v36, 16, v37
	v_and_b32_e32 v37, 0xffff0000, v37
	v_pk_add_f32 v[30:31], v[30:31], v[34:35]
	v_pk_add_f32 v[28:29], v[28:29], v[40:41]
	v_pk_add_f32 v[26:27], v[26:27], v[36:37]
	v_pk_add_f32 v[24:25], v[24:25], v[42:43]
	v_lshl_add_u64 v[34:35], v[38:39], 2, s[8:9]
	s_cbranch_vccnz .LBB0_3328
	v_lshl_add_u64 v[36:37], v[140:141], 2, v[34:35]
	global_store_dwordx4 v[36:37], v[28:31], off
	global_store_dwordx4 v[36:37], v[24:27], off offset:16
.LBB0_3328:
	v_cvt_pk_bf16_f32 v40, v28, v29
	v_cvt_pk_bf16_f32 v41, v30, v31
	v_cvt_pk_bf16_f32 v42, v24, v25
	v_cvt_pk_bf16_f32 v43, v26, v27
	global_store_dwordx4 v[32:33], v[40:43], off
	s_and_b64 vcc, exec, s[36:37]
	s_waitcnt vmcnt(10)
	v_mov_b64_e32 v[36:37], v[188:189]
	v_mov_b64_e32 v[38:39], v[190:191]
	v_lshlrev_b32_e32 v40, 16, v36
	v_and_b32_e32 v41, 0xffff0000, v36
	v_lshlrev_b32_e32 v36, 16, v37
	v_and_b32_e32 v37, 0xffff0000, v37
	v_lshlrev_b32_e32 v42, 16, v38
	v_and_b32_e32 v43, 0xffff0000, v38
	v_lshlrev_b32_e32 v38, 16, v39
	v_and_b32_e32 v39, 0xffff0000, v39
	v_pk_add_f32 v[22:23], v[22:23], v[36:37]
	v_pk_add_f32 v[20:21], v[20:21], v[40:41]
	v_pk_add_f32 v[18:19], v[18:19], v[38:39]
	v_pk_add_f32 v[16:17], v[16:17], v[42:43]
	s_cbranch_vccnz .LBB0_3330
	v_lshl_add_u64 v[34:35], v[140:141], 2, v[34:35]
	global_store_dwordx4 v[34:35], v[20:23], off offset:512
	global_store_dwordx4 v[34:35], v[16:19], off offset:528

; DI unsigned pk2(float lo, float hi) { f32x2 v = {lo, hi}; bf16x2_t b = __builtin_convertvector(v, bf16x2_t); return __builtin_bit_cast(unsigned, b); }
;     DI void operator()(const f32x4 (&acc)[2][2][4][2], const Unit& u, int wr, int wc, int fr, int fq) const {
;     ...
;         EPI_ROWS_BEGIN
;             float ss = 0.f;
; #pragma unroll
;             for (int bj = 0; bj < 2; ++bj) { const int col = colb + bj * HALF; bf16_t* xp = XB + (size_t)row * DM + col;
;                 float xv[8]; unpack8(*(const u32x4*)xp, xv);
;                 const f32x4 x0 = (f32x4){xv[0], xv[1], xv[2], xv[3]} + acc[ai][bj][m][0], x1 = (f32x4){xv[4], xv[5], xv[6], xv[7]} + acc[ai][bj][m][1];
;                 if (Y != nullptr) { float* yp = Y + (size_t)row * DM + col; *(f32x4*)yp = x0; *(f32x4*)(yp + 4) = x1; }
;                 u32x4 w; w.x = pk2(x0[0], x0[1]); w.y = pk2(x0[2], x0[3]); w.z = pk2(x1[0], x1[1]); w.w = pk2(x1[2], x1[3]); *(u32x4*)xp = w;
;                 ss += (x0[0] * x0[0] + x0[1] * x0[1]) + (x0[2] * x0[2] + x0[3] * x0[3]) + (x1[0] * x1[0] + x1[1] * x1[1]) + (x1[2] * x1[2] + x1[3] * x1[3]); }
.LBB0_3332:
	s_or_b64 exec, exec, s[38:39]
	v_add_u32_e32 v22, 0xb0, v142
	v_ashrrev_i32_e32 v23, 31, v22
	v_lshlrev_b64 v[16:17], 11, v[22:23]
	v_lshl_add_u64 v[16:17], s[10:11], 0, v[16:17]
	v_lshl_add_u64 v[16:17], v[140:141], 1, v[16:17]
	s_waitcnt lgkmcnt(0)
	v_lshlrev_b64 v[22:23], 10, v[22:23]
	s_and_b64 vcc, exec, s[36:37]
	s_waitcnt vmcnt(9)
	v_mov_b64_e32 v[18:19], v[192:193]
	v_mov_b64_e32 v[20:21], v[194:195]
	v_lshlrev_b32_e32 v24, 16, v18
	v_and_b32_e32 v25, 0xffff0000, v18
	v_lshlrev_b32_e32 v18, 16, v19
	v_and_b32_e32 v19, 0xffff0000, v19
	v_lshlrev_b32_e32 v26, 16, v20
	v_and_b32_e32 v27, 0xffff0000, v20
	v_lshlrev_b32_e32 v20, 16, v21
	v_and_b32_e32 v21, 0xffff0000, v21
	v_pk_add_f32 v[14:15], v[14:15], v[18:19]
	v_pk_add_f32 v[12:13], v[12:13], v[24:25]
	v_pk_add_f32 v[10:11], v[10:11], v[20:21]
	v_pk_add_f32 v[8:9], v[8:9], v[26:27]
	v_lshl_add_u64 v[18:19], v[22:23], 2, s[8:9]
	s_cbranch_vccnz .LBB0_3334
	v_lshl_add_u64 v[20:21], v[140:141], 2, v[18:19]
	global_store_dwordx4 v[20:21], v[12:15], off
	global_store_dwordx4 v[20:21], v[8:11], off offset:16
.LBB0_3334:
	v_cvt_pk_bf16_f32 v24, v12, v13
	v_cvt_pk_bf16_f32 v25, v14, v15
	v_cvt_pk_bf16_f32 v26, v8, v9
	v_cvt_pk_bf16_f32 v27, v10, v11
	global_store_dwordx4 v[16:17], v[24:27], off
	s_and_b64 vcc, exec, s[36:37]
	s_waitcnt vmcnt(8)
	v_mov_b64_e32 v[20:21], v[196:197]
	v_mov_b64_e32 v[22:23], v[198:199]
	v_lshlrev_b32_e32 v24, 16, v20
	v_and_b32_e32 v25, 0xffff0000, v20
	v_lshlrev_b32_e32 v20, 16, v21
	v_and_b32_e32 v21, 0xffff0000, v21
	v_lshlrev_b32_e32 v26, 16, v22
	v_and_b32_e32 v27, 0xffff0000, v22
	v_lshlrev_b32_e32 v22, 16, v23
	v_and_b32_e32 v23, 0xffff0000, v23
	v_pk_add_f32 v[6:7], v[6:7], v[20:21]
	v_pk_add_f32 v[4:5], v[4:5], v[24:25]
	v_pk_add_f32 v[2:3], v[2:3], v[22:23]
	v_pk_add_f32 v[0:1], v[0:1], v[26:27]
	s_cbranch_vccnz .LBB0_3336
	v_lshl_add_u64 v[18:19], v[140:141], 2, v[18:19]
	global_store_dwordx4 v[18:19], v[4:7], off offset:512
	global_store_dwordx4 v[18:19], v[0:3], off offset:528
